# S5 scan loops: the compiler's one-slot pads after v_pk_fma_f32 (dst-sel forwarding rule misapplied to packed f32) dropped from the dependent chains
# speedup vs baseline: 1.0055x; 1.0055x over previous
; #define LAS __attribute__((address_space(3)))
; __device__ __forceinline__ unsigned pk2(float lo, float hi) { return pg8::cvt_pk_bf16(lo, hi); }
; template <bool PASS_B> __device__ __forceinline__ void ssm_unit(const Args& a, LAS unsigned char* lds, const SsmTab& T, const u32x4 (&pre)[2], int l, size_t row0, int ntok, int gq, float& hr_io, float& hi_io, int wave) {
;     ...
;     for (int t0 = 0; t0 < ntok; t0 += 16) {
;         const int nt = (ntok - t0) < 16 ? (ntok - t0) : 16;
;         {
;             const bf16x8 uv = *(const LAS bf16x8*)(Ub + (t0 + r) * UST + wave * 16 + 8 * (qd & 1)); const bf16x8 ub = qd < 2 ? uv : (bf16x8){0, 0, 0, 0, 0, 0, 0, 0};
; #pragma unroll
;             for (int pt = 0; pt < 8; ++pt) { const f32x4 x = __builtin_amdgcn_mfma_f32_16x16x32_bf16(T.af[pt], ub, (f32x4){0.f, 0.f, 0.f, 0.f}, 0, 0, 0); *(LAS f32x4*)(Xs + r * XST + pt * 16 + 4 * qd) = x; }
;         }
;         asm volatile("s_waitcnt lgkmcnt(0)" ::: "memory");
;         {
;             typedef float f32x2 __attribute__((ext_vector_type(2)));
;             f32x2 xv[16];
; #pragma unroll
;             for (int tt = 0; tt < 16; ++tt) xv[tt] = *(const LAS f32x2*)(Xs + tt * XST + 2 * lane);
;             f32x2 h = {hr, hi}; const f32x2 a1 = {ar, ar}, a2 = {-ai, ai};
;             if (nt == 16) {
; #pragma unroll
;                 for (int tt = 0; tt < 16; ++tt) { const f32x2 hs = {h.y, h.x}; h = a1 * h + (a2 * hs + xv[tt]);
;                     if (PASS_B) *(LAS unsigned*)(hb + tt * HST + 2 * lane) = pk2(h.x, h.y); }
;             } else {
; #pragma unroll
;                 for (int tt = 0; tt < 16; ++tt) if (tt < nt) { const f32x2 hs = {h.y, h.x}; h = a1 * h + (a2 * hs + xv[tt]);
;                     if (PASS_B) *(LAS unsigned*)(hb + tt * HST + 2 * lane) = pk2(h.x, h.y); }
;             }
;             hr = h.x; hi = h.y;
.LBB0_355:
	s_or_b64 exec, exec, s[14:15]
	s_waitcnt lgkmcnt(0)
	v_mfma_f32_16x16x32_bf16 v[64:67], v[34:37], v[20:23], 0
	v_add_u32_e32 v26, 0x4800, v25
	s_add_i32 s16, s16, 16
	s_cmp_lt_u32 s16, 48
	v_mfma_f32_16x16x32_bf16 v[68:71], v[38:41], v[20:23], 0
	v_add_u32_e32 v0, 0x1100, v0
	s_nop 2
	ds_write_b128 v24, v[64:67] offset:17408
	v_mfma_f32_16x16x32_bf16 v[72:75], v[30:33], v[20:23], 0
	v_mfma_f32_16x16x32_bf16 v[76:79], v[42:45], v[20:23], 0
	s_nop 0
	ds_write_b128 v24, v[68:71] offset:17472
	s_nop 4
	ds_write_b128 v24, v[72:75] offset:17536
	ds_write_b128 v24, v[76:79] offset:17600
	v_mfma_f32_16x16x32_bf16 v[80:83], v[50:53], v[20:23], 0
	v_mfma_f32_16x16x32_bf16 v[64:67], v[54:57], v[20:23], 0
	v_mfma_f32_16x16x32_bf16 v[68:71], v[46:49], v[20:23], 0
	s_nop 5
	ds_write_b128 v24, v[80:83] offset:17664
	ds_write_b128 v24, v[64:67] offset:17728
	ds_write_b128 v24, v[68:71] offset:17792
	v_mfma_f32_16x16x32_bf16 v[20:23], v[58:61], v[20:23], 0
	s_nop 7
	ds_write_b128 v24, v[20:23] offset:17856
	s_waitcnt lgkmcnt(0)
	v_add_u32_e32 v20, 0x4000, v25
	ds_read2_b64 v[20:23], v20 offset0:128 offset1:194
	ds_read2_b64 v[64:67], v26 offset0:4 offset1:70
	ds_read2_b64 v[68:71], v26 offset0:136 offset1:202
	v_add_u32_e32 v26, 0x5000, v25
	ds_read2_b64 v[72:75], v26 offset0:12 offset1:78
	ds_read2_b64 v[76:79], v26 offset0:144 offset1:210
	v_add_u32_e32 v26, 0x5800, v25
	s_waitcnt lgkmcnt(4)
	v_pk_fma_f32 v[20:21], v[28:29], v[62:63], v[20:21] op_sel:[0,1,0] op_sel_hi:[1,0,1]
	ds_read2_b64 v[80:83], v26 offset0:20 offset1:86
	ds_read2_b64 v[84:87], v26 offset0:152 offset1:218
	v_pk_fma_f32 v[20:21], v[2:3], v[62:63], v[20:21]
	v_add_u32_e32 v26, 0x6000, v25
	v_pk_fma_f32 v[22:23], v[28:29], v[20:21], v[22:23] op_sel:[0,1,0] op_sel_hi:[1,0,1]
	ds_read2_b64 v[88:91], v26 offset0:28 offset1:94
	v_pk_fma_f32 v[20:21], v[2:3], v[20:21], v[22:23]
	s_waitcnt lgkmcnt(0)
	s_waitcnt lgkmcnt(6)
	v_pk_fma_f32 v[22:23], v[28:29], v[20:21], v[64:65] op_sel:[0,1,0] op_sel_hi:[1,0,1]
	v_pk_fma_f32 v[20:21], v[2:3], v[20:21], v[22:23]
	v_pk_fma_f32 v[22:23], v[28:29], v[20:21], v[66:67] op_sel:[0,1,0] op_sel_hi:[1,0,1]
	v_pk_fma_f32 v[20:21], v[2:3], v[20:21], v[22:23]
	s_waitcnt lgkmcnt(5)
	v_pk_fma_f32 v[22:23], v[28:29], v[20:21], v[68:69] op_sel:[0,1,0] op_sel_hi:[1,0,1]
	v_pk_fma_f32 v[20:21], v[2:3], v[20:21], v[22:23]
	v_pk_fma_f32 v[22:23], v[28:29], v[20:21], v[70:71] op_sel:[0,1,0] op_sel_hi:[1,0,1]
	v_pk_fma_f32 v[20:21], v[2:3], v[20:21], v[22:23]
	s_waitcnt lgkmcnt(4)
	v_pk_fma_f32 v[22:23], v[28:29], v[20:21], v[72:73] op_sel:[0,1,0] op_sel_hi:[1,0,1]
	v_pk_fma_f32 v[20:21], v[2:3], v[20:21], v[22:23]
	v_pk_fma_f32 v[22:23], v[28:29], v[20:21], v[74:75] op_sel:[0,1,0] op_sel_hi:[1,0,1]
	v_pk_fma_f32 v[20:21], v[2:3], v[20:21], v[22:23]
	s_waitcnt lgkmcnt(3)
	v_pk_fma_f32 v[22:23], v[28:29], v[20:21], v[76:77] op_sel:[0,1,0] op_sel_hi:[1,0,1]
	v_pk_fma_f32 v[20:21], v[2:3], v[20:21], v[22:23]
	v_pk_fma_f32 v[22:23], v[28:29], v[20:21], v[78:79] op_sel:[0,1,0] op_sel_hi:[1,0,1]
	v_pk_fma_f32 v[20:21], v[2:3], v[20:21], v[22:23]
	s_waitcnt lgkmcnt(2)
	v_pk_fma_f32 v[22:23], v[28:29], v[20:21], v[80:81] op_sel:[0,1,0] op_sel_hi:[1,0,1]
	v_pk_fma_f32 v[20:21], v[2:3], v[20:21], v[22:23]
	v_pk_fma_f32 v[22:23], v[28:29], v[20:21], v[82:83] op_sel:[0,1,0] op_sel_hi:[1,0,1]
	v_pk_fma_f32 v[20:21], v[2:3], v[20:21], v[22:23]
	s_waitcnt lgkmcnt(1)
	v_pk_fma_f32 v[22:23], v[28:29], v[20:21], v[84:85] op_sel:[0,1,0] op_sel_hi:[1,0,1]
	v_pk_fma_f32 v[20:21], v[2:3], v[20:21], v[22:23]
	v_pk_fma_f32 v[22:23], v[28:29], v[20:21], v[86:87] op_sel:[0,1,0] op_sel_hi:[1,0,1]
	v_pk_fma_f32 v[20:21], v[2:3], v[20:21], v[22:23]
	s_waitcnt lgkmcnt(0)
	v_pk_fma_f32 v[22:23], v[28:29], v[20:21], v[88:89] op_sel:[0,1,0] op_sel_hi:[1,0,1]
	v_pk_fma_f32 v[20:21], v[2:3], v[20:21], v[22:23]
	v_pk_fma_f32 v[22:23], v[28:29], v[20:21], v[90:91] op_sel:[0,1,0] op_sel_hi:[1,0,1]
	v_pk_fma_f32 v[62:63], v[2:3], v[20:21], v[22:23]
	s_cbranch_scc0 .LBB0_358

; #define LAS __attribute__((address_space(3)))
; __device__ __forceinline__ unsigned pk2(float lo, float hi) { return pg8::cvt_pk_bf16(lo, hi); }
; template <bool PASS_B> __device__ __forceinline__ void ssm_unit(const Args& a, LAS unsigned char* lds, const SsmTab& T, const u32x4 (&pre)[2], int l, size_t row0, int ntok, int gq, float& hr_io, float& hi_io, int wave) {
;     ...
;     for (int t0 = 0; t0 < ntok; t0 += 16) {
;         const int nt = (ntok - t0) < 16 ? (ntok - t0) : 16;
;         {
;             const bf16x8 uv = *(const LAS bf16x8*)(Ub + (t0 + r) * UST + wave * 16 + 8 * (qd & 1)); const bf16x8 ub = qd < 2 ? uv : (bf16x8){0, 0, 0, 0, 0, 0, 0, 0};
; #pragma unroll
;             for (int pt = 0; pt < 8; ++pt) { const f32x4 x = __builtin_amdgcn_mfma_f32_16x16x32_bf16(T.af[pt], ub, (f32x4){0.f, 0.f, 0.f, 0.f}, 0, 0, 0); *(LAS f32x4*)(Xs + r * XST + pt * 16 + 4 * qd) = x; }
;         }
;         asm volatile("s_waitcnt lgkmcnt(0)" ::: "memory");
;         {
;             typedef float f32x2 __attribute__((ext_vector_type(2)));
;             f32x2 xv[16];
; #pragma unroll
;             for (int tt = 0; tt < 16; ++tt) xv[tt] = *(const LAS f32x2*)(Xs + tt * XST + 2 * lane);
;             f32x2 h = {hr, hi}; const f32x2 a1 = {ar, ar}, a2 = {-ai, ai};
;             if (nt == 16) {
; #pragma unroll
;                 for (int tt = 0; tt < 16; ++tt) { const f32x2 hs = {h.y, h.x}; h = a1 * h + (a2 * hs + xv[tt]);
;                     if (PASS_B) *(LAS unsigned*)(hb + tt * HST + 2 * lane) = pk2(h.x, h.y); }
;             } else {
; #pragma unroll
;                 for (int tt = 0; tt < 16; ++tt) if (tt < nt) { const f32x2 hs = {h.y, h.x}; h = a1 * h + (a2 * hs + xv[tt]);
;                     if (PASS_B) *(LAS unsigned*)(hb + tt * HST + 2 * lane) = pk2(h.x, h.y); }
.LBB0_469:
	s_or_b64 exec, exec, s[8:9]
	s_waitcnt lgkmcnt(0)
	v_mfma_f32_16x16x32_bf16 v[94:97], v[32:35], v[12:15], 0
	v_add_u32_e32 v87, 0x5800, v84
	s_add_i32 s10, s10, 16
	s_mov_b64 s[8:9], 0x4000
	v_mfma_f32_16x16x32_bf16 v[98:101], v[36:39], v[12:15], 0
	v_add_u32_e32 v19, 0x1100, v19
	s_nop 2
	ds_write_b128 v0, v[94:97] offset:17408
	s_cmp_lt_u32 s10, 48
	v_mfma_f32_16x16x32_bf16 v[102:105], v[28:31], v[12:15], 0
	v_mfma_f32_16x16x32_bf16 v[106:109], v[40:43], v[12:15], 0
	ds_write_b128 v0, v[98:101] offset:17472
	s_nop 5
	ds_write_b128 v0, v[102:105] offset:17536
	ds_write_b128 v0, v[106:109] offset:17600
	v_mfma_f32_16x16x32_bf16 v[110:113], v[48:51], v[12:15], 0
	v_mfma_f32_16x16x32_bf16 v[94:97], v[52:55], v[12:15], 0
	v_mfma_f32_16x16x32_bf16 v[98:101], v[44:47], v[12:15], 0
	s_nop 5
	ds_write_b128 v0, v[110:113] offset:17664
	ds_write_b128 v0, v[94:97] offset:17728
	ds_write_b128 v0, v[98:101] offset:17792
	v_mfma_f32_16x16x32_bf16 v[12:15], v[56:59], v[12:15], 0
	s_nop 7
	ds_write_b128 v0, v[12:15] offset:17856
	s_waitcnt lgkmcnt(0)
	v_add_u32_e32 v12, 0x4000, v84
	ds_read2_b64 v[12:15], v12 offset0:128 offset1:194
	ds_read2_b64 v[94:97], v87 offset0:152 offset1:218
	ds_read2_b64 v[98:101], v87 offset0:20 offset1:86
	v_add_u32_e32 v87, 0x5000, v84
	ds_read2_b64 v[102:105], v87 offset0:144 offset1:210
	ds_read2_b64 v[106:109], v87 offset0:12 offset1:78
	v_add_u32_e32 v87, 0x4800, v84
	ds_read2_b64 v[110:113], v87 offset0:136 offset1:202
	ds_read2_b64 v[114:117], v87 offset0:4 offset1:70
	s_waitcnt lgkmcnt(6)
	v_pk_fma_f32 v[12:13], v[2:3], v[82:83], v[12:13] op_sel:[0,1,0] op_sel_hi:[1,0,1]
	v_add_u32_e32 v87, 0x6000, v84
	v_pk_fma_f32 v[12:13], v[80:81], v[82:83], v[12:13]
	ds_read2_b64 v[118:121], v87 offset0:28 offset1:94
	v_pk_fma_f32 v[14:15], v[2:3], v[12:13], v[14:15] op_sel:[0,1,0] op_sel_hi:[1,0,1]
	v_cvt_pk_bf16_f32 v82, v12, v13
	ds_write_b32 v85, v82
	v_pk_fma_f32 v[12:13], v[80:81], v[12:13], v[14:15]
	v_cvt_pk_bf16_f32 v14, v12, v13
	ds_write_b32 v85, v14 offset:272
	s_waitcnt lgkmcnt(3)
	v_pk_fma_f32 v[14:15], v[2:3], v[12:13], v[114:115] op_sel:[0,1,0] op_sel_hi:[1,0,1]
	v_pk_fma_f32 v[12:13], v[80:81], v[12:13], v[14:15]
	v_cvt_pk_bf16_f32 v14, v12, v13
	ds_write_b32 v85, v14 offset:544
	v_pk_fma_f32 v[14:15], v[2:3], v[12:13], v[116:117] op_sel:[0,1,0] op_sel_hi:[1,0,1]
	v_pk_fma_f32 v[12:13], v[80:81], v[12:13], v[14:15]
	v_cvt_pk_bf16_f32 v14, v12, v13
	ds_write_b32 v85, v14 offset:816
	v_pk_fma_f32 v[14:15], v[2:3], v[12:13], v[110:111] op_sel:[0,1,0] op_sel_hi:[1,0,1]
	v_pk_fma_f32 v[12:13], v[80:81], v[12:13], v[14:15]
	v_cvt_pk_bf16_f32 v14, v12, v13
	ds_write_b32 v85, v14 offset:1088
	v_pk_fma_f32 v[14:15], v[2:3], v[12:13], v[112:113] op_sel:[0,1,0] op_sel_hi:[1,0,1]
	v_pk_fma_f32 v[12:13], v[80:81], v[12:13], v[14:15]
	v_cvt_pk_bf16_f32 v14, v12, v13
	ds_write_b32 v85, v14 offset:1360
	v_pk_fma_f32 v[14:15], v[2:3], v[12:13], v[106:107] op_sel:[0,1,0] op_sel_hi:[1,0,1]
	v_pk_fma_f32 v[12:13], v[80:81], v[12:13], v[14:15]
	v_cvt_pk_bf16_f32 v14, v12, v13
	ds_write_b32 v85, v14 offset:1632
	v_pk_fma_f32 v[14:15], v[2:3], v[12:13], v[108:109] op_sel:[0,1,0] op_sel_hi:[1,0,1]
	v_pk_fma_f32 v[12:13], v[80:81], v[12:13], v[14:15]
	v_cvt_pk_bf16_f32 v14, v12, v13
	ds_write_b32 v85, v14 offset:1904
	v_pk_fma_f32 v[14:15], v[2:3], v[12:13], v[102:103] op_sel:[0,1,0] op_sel_hi:[1,0,1]
	v_pk_fma_f32 v[12:13], v[80:81], v[12:13], v[14:15]
	v_cvt_pk_bf16_f32 v14, v12, v13
	ds_write_b32 v85, v14 offset:2176
	v_pk_fma_f32 v[14:15], v[2:3], v[12:13], v[104:105] op_sel:[0,1,0] op_sel_hi:[1,0,1]
	v_pk_fma_f32 v[12:13], v[80:81], v[12:13], v[14:15]
	v_cvt_pk_bf16_f32 v14, v12, v13
	ds_write_b32 v85, v14 offset:2448
	v_pk_fma_f32 v[14:15], v[2:3], v[12:13], v[98:99] op_sel:[0,1,0] op_sel_hi:[1,0,1]
	v_pk_fma_f32 v[12:13], v[80:81], v[12:13], v[14:15]
	v_cvt_pk_bf16_f32 v14, v12, v13
	ds_write_b32 v85, v14 offset:2720
	v_pk_fma_f32 v[14:15], v[2:3], v[12:13], v[100:101] op_sel:[0,1,0] op_sel_hi:[1,0,1]
	v_pk_fma_f32 v[12:13], v[80:81], v[12:13], v[14:15]
	v_cvt_pk_bf16_f32 v14, v12, v13
	ds_write_b32 v85, v14 offset:2992
	v_pk_fma_f32 v[14:15], v[2:3], v[12:13], v[94:95] op_sel:[0,1,0] op_sel_hi:[1,0,1]
	v_pk_fma_f32 v[12:13], v[80:81], v[12:13], v[14:15]
	v_cvt_pk_bf16_f32 v14, v12, v13
	ds_write_b32 v85, v14 offset:3264
	v_pk_fma_f32 v[14:15], v[2:3], v[12:13], v[96:97] op_sel:[0,1,0] op_sel_hi:[1,0,1]
	v_pk_fma_f32 v[12:13], v[80:81], v[12:13], v[14:15]
	v_cvt_pk_bf16_f32 v14, v12, v13
	ds_write_b32 v85, v14 offset:3536
	s_waitcnt lgkmcnt(14)
; #define LAS __attribute__((address_space(3)))
; __device__ __forceinline__ float bf2f(unsigned short b) { return __uint_as_float(((unsigned)b) << 16); }
; __device__ __forceinline__ unsigned pk2(float lo, float hi) { return pg8::cvt_pk_bf16(lo, hi); }
; __device__ __forceinline__ unsigned short f2bf(float f) { return (unsigned short)(pg8::cvt_pk_bf16(f, 0.f) & 0xffffu); }
; template <bool PASS_B> __device__ __forceinline__ void ssm_unit(const Args& a, LAS unsigned char* lds, const SsmTab& T, const u32x4 (&pre)[2], int l, size_t row0, int ntok, int gq, float& hr_io, float& hi_io, int wave) {
;     ...
;                 for (int tt = 0; tt < 16; ++tt) { const f32x2 hs = {h.y, h.x}; h = a1 * h + (a2 * hs + xv[tt]);
;                     if (PASS_B) *(LAS unsigned*)(hb + tt * HST + 2 * lane) = pk2(h.x, h.y); }
;             } else {
; #pragma unroll
;                 for (int tt = 0; tt < 16; ++tt) if (tt < nt) { const f32x2 hs = {h.y, h.x}; h = a1 * h + (a2 * hs + xv[tt]);
;                     if (PASS_B) *(LAS unsigned*)(hb + tt * HST + 2 * lane) = pk2(h.x, h.y); }
;             }
;             hr = h.x; hi = h.y;
;         }
;         if (PASS_B) {
;             f32x4 acc = {0.f, 0.f, 0.f, 0.f};
;             asm volatile("s_waitcnt lgkmcnt(0)" ::: "memory");
; #pragma unroll
;             for (int s = 0; s < 4; ++s) { const bf16x8 hf = *(const LAS bf16x8*)(hb + r * HST + s * 32 + qd * 8); acc = __builtin_amdgcn_mfma_f32_16x16x32_bf16(hf, T.cf[s], acc, 0, 0, 0); }
;             asm volatile("s_waitcnt lgkmcnt(0)" ::: "memory");
;             bf16_t* yo = (bf16_t*)(a.ws + WS_B + HALFROWS);
; #pragma unroll
;             for (int k = 0; k < 4; ++k) { const int tt = 4 * qd + k;
;                 if (tt < nt) { const float y = acc[k] + dsk * bf2f(Ub[(t0 + tt) * UST + wave * 16 + r]); yo[(row0 + t0 + tt) * 512 + g * 16 + r] = f2bf(gelu_tanh(y)); } }
;         }
;         asm volatile("s_waitcnt lgkmcnt(0)" ::: "memory");
	v_pk_fma_f32 v[14:15], v[2:3], v[12:13], v[118:119] op_sel:[0,1,0] op_sel_hi:[1,0,1]
	v_pk_fma_f32 v[12:13], v[80:81], v[12:13], v[14:15]
	v_cvt_pk_bf16_f32 v14, v12, v13
	ds_write_b32 v85, v14 offset:3808
	v_pk_fma_f32 v[14:15], v[2:3], v[12:13], v[120:121] op_sel:[0,1,0] op_sel_hi:[1,0,1]
	v_pk_fma_f32 v[82:83], v[80:81], v[12:13], v[14:15]
	v_cvt_pk_bf16_f32 v12, v82, v83
	ds_write_b32 v85, v12 offset:4080
	s_waitcnt lgkmcnt(0)
	ds_read_b128 v[12:15], v86
	ds_read_b128 v[94:97], v86 offset:64
	s_waitcnt lgkmcnt(1)
	v_mfma_f32_16x16x32_bf16 v[12:15], v[12:15], v[60:63], 0
	ds_read_b128 v[98:101], v86 offset:128
	s_waitcnt lgkmcnt(1)
	v_mfma_f32_16x16x32_bf16 v[12:15], v[94:97], v[64:67], v[12:15]
	ds_read_b128 v[94:97], v86 offset:192
	s_waitcnt lgkmcnt(0)
	ds_read_u16 v87, v18
	s_waitcnt lgkmcnt(2)
	v_mfma_f32_16x16x32_bf16 v[12:15], v[98:101], v[68:71], v[12:15]
	s_waitcnt lgkmcnt(0)
	v_lshlrev_b32_e32 v87, 16, v87
	v_mfma_f32_16x16x32_bf16 v[12:15], v[94:97], v[72:75], v[12:15]
	s_nop 7
	v_fma_f32 v12, v90, v87, v12
	v_mul_f32_e32 v87, v12, v12
	v_fmamk_f32 v87, v87, 0xbdd2d3e7, v214
	v_mul_f32_e32 v87, v12, v87
	v_exp_f32_e32 v87, v87
	s_nop 0
	v_add_f32_e32 v87, 1.0, v87
	v_rcp_f32_e32 v87, v87
	s_nop 0
	v_mul_f32_e32 v12, v12, v87
	v_cvt_pk_bf16_f32 v12, v12, v1
	ds_read_u16 v87, v18 offset:272
	global_store_short v[16:17], v12, off offset:-2048
	s_waitcnt lgkmcnt(0)
	v_lshlrev_b32_e32 v87, 16, v87
	v_fma_f32 v13, v90, v87, v13
	v_mul_f32_e32 v87, v13, v13
	v_fmamk_f32 v87, v87, 0xbdd2d3e7, v214
	v_mul_f32_e32 v87, v13, v87
	v_exp_f32_e32 v87, v87
	s_nop 0
	v_add_f32_e32 v87, 1.0, v87
	v_rcp_f32_e32 v87, v87
	s_nop 0
	v_mul_f32_e32 v12, v13, v87
	v_cvt_pk_bf16_f32 v12, v12, v1
	ds_read_u16 v13, v18 offset:544
	global_store_short v[16:17], v12, off offset:-1024
	s_waitcnt lgkmcnt(0)
	v_lshlrev_b32_e32 v13, 16, v13
	v_fma_f32 v13, v90, v13, v14
	v_mul_f32_e32 v14, v13, v13
	v_fmamk_f32 v14, v14, 0xbdd2d3e7, v214
	v_mul_f32_e32 v14, v13, v14
	v_exp_f32_e32 v14, v14
	s_nop 0
	v_add_f32_e32 v14, 1.0, v14
	v_rcp_f32_e32 v14, v14
	s_nop 0
	v_mul_f32_e32 v12, v13, v14
	v_cvt_pk_bf16_f32 v12, v12, v1
	ds_read_u16 v13, v18 offset:816
	global_store_short v[16:17], v12, off
	v_add_u32_e32 v18, 0x1100, v18
	s_waitcnt lgkmcnt(0)
	v_lshlrev_b32_e32 v13, 16, v13
	v_fmac_f32_e32 v15, v90, v13
	v_mul_f32_e32 v13, v15, v15
	v_fmamk_f32 v13, v13, 0xbdd2d3e7, v214
	v_mul_f32_e32 v13, v15, v13
	v_exp_f32_e32 v13, v13
	s_nop 0
	v_add_f32_e32 v13, 1.0, v13
	v_rcp_f32_e32 v13, v13
	s_nop 0
	v_mul_f32_e32 v12, v15, v13
	v_cvt_pk_bf16_f32 v12, v12, v1
	global_store_short v[16:17], v12, off offset:1024
	s_waitcnt lgkmcnt(0)
	v_lshl_add_u64 v[16:17], v[16:17], 0, s[8:9]
	s_cbranch_scc0 .LBB0_472
